# in-proj phase start de-serialised: the 16 row-statistic loads are issued, the GEMM prologue (address setup + first 8 tile DMAs) runs while they fly, then the sums/rsqrt/LDS stash are computed; stash r
# speedup vs baseline: 1.0002x; 1.0002x over previous
; #define LAS __attribute__((address_space(3)))
; __device__ __forceinline__ int fresh_tid(const Frame& F) { unsigned m_ = ~0u; asm volatile("" : "+s"(m_)); return F.wave * 64 + (int)__builtin_amdgcn_mbcnt_hi(m_, __builtin_amdgcn_mbcnt_lo(m_, 0u)); }
; __device__ __forceinline__ void stash_rstd(const Frame& F, const float* slots, int nslot, int panel, float inv_dim) {
;     const int tid = fresh_tid(F);
;     __syncthreads();
;     if (tid < 256) { const f32x4* p = (const f32x4*)(slots + (size_t)(panel * 256 + tid) * nslot); float s = 0.f;
;         for (int j = 0; j < nslot / 4; ++j) { const f32x4 t = p[j]; s += (t[0] + t[1]) + (t[2] + t[3]); }
;         ((LAS float*)(F.lds + STASH_OFF))[tid] = __builtin_amdgcn_rsqf(s * inv_dim + EPS); }
.LBB0_129:
	s_mov_b32 s2, -1
	s_nop 0
	v_mbcnt_lo_u32_b32 v76, s2, 0
	v_mbcnt_hi_u32_b32 v76, s2, v76
	v_add_u32_e32 v76, s95, v76
	s_movk_i32 s2, 0x100
	v_cmp_gt_i32_e32 vcc, s2, v76
	s_barrier
	s_and_saveexec_b64 s[2:3], vcc
	s_cbranch_execz .Lst_p1end
	s_waitcnt vmcnt(7)
	v_lshl_add_u32 v10, s25, 8, v76
	v_ashrrev_i32_e32 v11, 31, v10
	v_readlane_b32 s4, v255, 24
	v_lshlrev_b64 v[10:11], 8, v[10:11]
	v_readlane_b32 s5, v255, 25
	v_lshl_add_u32 v76, v76, 2, 0
	v_add_u32_e32 v76, 0x26000, v76
	v_lshl_add_u64 v[66:67], s[4:5], 0, v[10:11]
	s_mov_b64 s[4:5], 0x17300000
	v_lshl_add_u64 v[70:71], v[66:67], 0, s[4:5]
	v_add_co_u32_e32 v66, vcc, 0x17300000, v66
	global_load_dwordx4 v[10:13], v[70:71], off offset:16
	global_load_dwordx4 v[14:17], v[70:71], off offset:32
	global_load_dwordx4 v[18:21], v[70:71], off offset:48
	global_load_dwordx4 v[22:25], v[70:71], off offset:64
	global_load_dwordx4 v[26:29], v[70:71], off offset:80
	global_load_dwordx4 v[30:33], v[70:71], off offset:96
	global_load_dwordx4 v[34:37], v[70:71], off offset:112
	global_load_dwordx4 v[38:41], v[70:71], off offset:128
	global_load_dwordx4 v[42:45], v[70:71], off offset:144
	global_load_dwordx4 v[46:49], v[70:71], off offset:160
	global_load_dwordx4 v[50:53], v[70:71], off offset:176
	global_load_dwordx4 v[54:57], v[70:71], off offset:192
	global_load_dwordx4 v[58:61], v[70:71], off offset:224
	global_load_dwordx4 v[62:65], v[70:71], off offset:208
	v_addc_co_u32_e32 v67, vcc, 0, v67, vcc
	global_load_dwordx4 v[66:69], v[66:67], off
	s_nop 0
	global_load_dwordx4 v[70:73], v[70:71], off offset:240

; #define PG8_BAR __builtin_amdgcn_s_barrier()
; template <class Epi, class Sched, bool ALIGN_EPI, bool SP2>
; __device__ __forceinline__ void gemm_phase(LAS unsigned char* lds, const Gemm g, const Sched& S, const Epi& E, int tid_in) {
;     ...
;     const int tid = tid_, wid = __builtin_amdgcn_readfirstlane(tid >> 6), lane = tid & 63, wr = wid >> 2, wc = wid & 3, fr = lane & 15, fq = lane >> 4;
;     const int K = g.K, nt = K / BK;
;     unsigned voffA[2], voffB[2];
; #pragma unroll
;     for (int i = 0; i < 2; ++i) { int R, C; stage_rc(tid * 16 + i * 8192, R, C); const int Rb = Epi::PERM ? ((Epi::CMAP ? 64 * (R >> 5) : (R & ~31)) + perm32(R & 31)) : R;
;         voffA[i] = (unsigned)(R * g.lda + C) * 2u; voffB[i] = (unsigned)(Rb * g.ldb + C) * 2u; }
;     const unsigned kstep = (unsigned)(BK * 2);
;     const unsigned hstepA = (unsigned)HALF * g.lda * 2, hstepB = (unsigned)(Epi::CMAP ? 32 : HALF) * g.ldb * 2;
;     const unsigned tstepA = 2 * hstepA, tstepB = (unsigned)2 * HALF * g.ldb * 2;
;     const __amdgpu_buffer_rsrc_t R_voffA = __builtin_amdgcn_make_buffer_rsrc((void*)g.A, (short)0, 0x7ffffff0, 0x00020000), R_voffB = __builtin_amdgcn_make_buffer_rsrc((void*)g.Bt, (short)0, 0x7ffffff0, 0x00020000);
;     const unsigned ldsw = (unsigned)wid * 1024u;
;     const int aoff = lds_byte(wr * 64 + fr, fq * 8), boff = lds_byte(wc * 32 + fr, fq * 8);
;     ...
;     Unit cur, nxt; int ui = 0;
;     if (!S.next(0, cur)) return;
;     f32x4 acc[2][2][4][2];
; #pragma unroll
;     for (int a = 0; a < 2; ++a)
; #pragma unroll
;         for (int b = 0; b < 2; ++b)
; #pragma unroll
;             for (int m = 0; m < 4; ++m)
; #pragma unroll
;                 for (int n = 0; n < 2; ++n) acc[a][b][m][n] = (f32x4){0.f, 0.f, 0.f, 0.f};
;     bf16x8 At[4][2], B0[2][2], B1[2][2]; i32x8v At8[4], B08[2], B18[2];
;     unsigned cA = (unsigned)cur.pm * tstepA, cB = (unsigned)cur.pn * tstepB;
;     if constexpr (SP2) {
;         PG8_STAGE(PG8_SB(0, 0), cB, voffB); PG8_STAGE(PG8_SB(0, 1), cB + hstepB, voffB); PG8_STAGE(PG8_SA(0, 0), cA, voffA); PG8_STAGE(PG8_SA(0, 1), cA + hstepA, voffA);
;         if (wr == 1) PG8_BAR;
;         PG8_WAIT_V(2); PG8_BAR;
; __device__ __forceinline__ void stash_rstd(const Frame& F, const float* slots, int nslot, int panel, float inv_dim) {
;     ...
;     if (tid < 256) { const f32x4* p = (const f32x4*)(slots + (size_t)(panel * 256 + tid) * nslot); float s = 0.f;
.LBB0_131:
	s_or_b64 exec, exec, s[2:3]
	s_lshl_b32 s2, s65, 2
	s_and_b32 s2, s2, 4
	s_ashr_i32 s3, s65, 6
	s_add_i32 s30, s2, s3
	s_bfe_u32 s31, s65, 0x20001
	v_readlane_b32 s6, v255, 24
	v_readlane_b32 s7, v255, 25
	s_add_u32 s40, s6, 0x18000000
	s_addc_u32 s4, s7, 0
	s_mul_i32 s3, s48, 0x6000000
	s_mul_hi_i32 s2, s48, 0x6000000
	s_add_u32 s3, s6, s3
	s_addc_u32 s2, s7, s2
	s_add_u32 s44, s3, 0x1000000
	s_addc_u32 s17, s2, 0
	s_mov_b32 s2, -1
	s_waitcnt lgkmcnt(0)
	s_barrier
	s_waitcnt vmcnt(22)
	v_mov_b32_e32 v9, 1
	v_mbcnt_lo_u32_b32 v0, s2, 0
	v_mbcnt_hi_u32_b32 v0, s2, v0
	v_add_u32_e32 v0, s95, v0
	s_lshl_b32 s5, s31, 3
	v_bfe_i32 v4, v0, 27, 1
	v_lshlrev_b32_e32 v2, 4, v0
	v_lshrrev_b32_e32 v4, 22, v4
	v_add_u32_e32 v4, v2, v4
	v_and_b32_e32 v4, 0xfffffc00, v4
	v_sub_u32_e32 v4, v2, v4
	v_ashrrev_i32_e32 v3, 31, v0
	v_lshrrev_b32_e32 v5, 4, v4
	v_lshrrev_b32_e32 v3, 26, v3
	v_bitop3_b32 v4, v5, v4, 32 bitop3:0x6c
	v_add_u32_e32 v3, v0, v3
	v_ashrrev_i32_e32 v6, 31, v4
	v_ashrrev_i32_e32 v3, 6, v3
	v_lshrrev_b32_e32 v6, 26, v6
	v_lshlrev_b32_e32 v5, 3, v3
	v_add_u32_e32 v6, v4, v6
	v_and_b32_e32 v5, -16, v5
	v_ashrrev_i32_e32 v7, 6, v6
	v_and_b32_e32 v6, 0xc0, v6
	v_add_u32_e32 v5, v7, v5
	v_sub_u32_e32 v4, v4, v6
	v_lshlrev_b32_e32 v3, 5, v3
	v_ashrrev_i16_sdwa v4, v9, sext(v4) dst_sel:DWORD dst_unused:UNUSED_PAD src0_sel:DWORD src1_sel:BYTE_0
	v_lshlrev_b32_e32 v6, 1, v5
	v_lshrrev_b32_e32 v8, 2, v5
	v_and_b32_e32 v3, 32, v3
	v_bfe_i32 v4, v4, 0, 16
	v_and_b32_e32 v8, 4, v8
	v_and_b32_e32 v7, 3, v7
	v_and_b32_e32 v6, 0x7ffd8, v6
	v_or3_b32 v6, v7, v8, v6
	v_add_lshl_u32 v3, v3, v4, 1
	v_add_u32_e32 v2, 0x2000, v2
	v_lshl_add_u32 v115, v5, 13, v3
	v_lshl_add_u32 v188, v6, 13, v3
	v_ashrrev_i32_e32 v3, 31, v2
	v_lshrrev_b32_e32 v3, 22, v3
	v_add_u32_e32 v3, v2, v3
	v_ashrrev_i32_e32 v3, 10, v3
	v_mul_i32_i24_e32 v4, 0x400, v3
	v_sub_u32_e32 v2, v2, v4
	v_lshrrev_b32_e32 v4, 4, v2
	v_bitop3_b32 v2, v4, v2, 32 bitop3:0x6c
	v_ashrrev_i32_e32 v5, 31, v2
	v_lshrrev_b32_e32 v5, 26, v5
	v_readfirstlane_b32 s2, v0
	v_lshlrev_b32_e32 v4, 3, v3
	v_add_u32_e32 v5, v2, v5
	s_ashr_i32 s3, s2, 6
	v_and_b32_e32 v4, -16, v4
	v_ashrrev_i32_e32 v6, 6, v5
	v_and_b32_e32 v5, 0xc0, v5
	v_add_u32_e32 v4, v6, v4
	v_sub_u32_e32 v2, v2, v5
	s_lshl_b32 s6, s3, 10
	v_lshlrev_b32_e32 v3, 5, v3
	v_ashrrev_i16_sdwa v2, v9, sext(v2) dst_sel:DWORD dst_unused:UNUSED_PAD src0_sel:DWORD src1_sel:BYTE_0
	v_lshlrev_b32_e32 v5, 1, v4
	v_lshrrev_b32_e32 v7, 2, v4
	s_add_i32 s15, s6, 0
	v_and_b32_e32 v3, 32, v3
	v_bfe_i32 v2, v2, 0, 16
	v_and_b32_e32 v7, 4, v7
	v_and_b32_e32 v6, 3, v6
	v_and_b32_e32 v5, 0x7ffd8, v5
	s_add_i32 s66, s5, s30
	s_add_i32 s68, s15, 0x10000
	v_or3_b32 v5, v6, v7, v5
	v_add_lshl_u32 v2, v3, v2, 1
	s_and_b32 s45, s17, 0xffff
	s_mov_b32 s46, s86
	s_mov_b32 s47, s87
	s_lshl_b32 s71, s66, 21
	s_mov_b32 m0, s68
	s_add_i32 s69, s15, 0x12000
	v_lshl_add_u32 v190, v5, 13, v2
	buffer_load_dwordx4 v188, s[44:47], s71 offen lds
	s_mov_b32 m0, s69
	s_add_i32 s70, s15, 0x14000
	buffer_load_dwordx4 v190, s[44:47], s71 offen lds
	s_and_b32 s41, s4, 0xffff
	s_or_b32 s4, s71, 0x40000
	s_mov_b32 m0, s70
	s_add_i32 s72, s15, 0x16000
	buffer_load_dwordx4 v188, s[44:47], s4 offen lds
	s_mov_b32 m0, s72
	s_mov_b32 s84, s40
	s_mov_b32 s85, s41
	buffer_load_dwordx4 v190, s[44:47], s4 offen lds
	s_lshl_b32 s76, s25, 21
	s_mov_b32 m0, s15
	s_add_i32 s73, s15, 0x2000
	v_lshl_add_u32 v189, v4, 13, v2
	buffer_load_dwordx4 v115, s[84:87], s76 offen lds
	s_mov_b32 m0, s73
	s_add_i32 s74, s15, 0x4000
	buffer_load_dwordx4 v189, s[84:87], s76 offen lds
	s_or_b32 s4, s76, 0x100000
	s_mov_b32 m0, s74
	s_add_i32 s75, s15, 0x6000
	buffer_load_dwordx4 v115, s[84:87], s4 offen lds
	s_mov_b32 m0, s75
	s_mov_b32 s42, s86
	buffer_load_dwordx4 v189, s[84:87], s4 offen lds
	s_cmpk_lt_u32 s95, 0x100
	s_cbranch_scc0 .Lst_p2end
	s_waitcnt vmcnt(8)
	v_mov_b32_e32 v74, v11
	v_mov_b32_e32 v75, v12
	v_mov_b32_e32 v11, v13
	v_add_f32_e32 v12, v14, v15
	v_add_f32_e32 v14, v16, v17
	v_mov_b32_e32 v13, v20
	v_mov_b32_e32 v15, v21
	v_mov_b32_e32 v20, v23
	v_mov_b32_e32 v21, v24
	v_mov_b32_e32 v23, v25
	v_add_f32_e32 v24, v26, v27
	v_add_f32_e32 v26, v28, v29
	v_mov_b32_e32 v28, v35
	v_mov_b32_e32 v29, v36
	v_mov_b32_e32 v35, v37
	v_add_f32_e32 v36, v40, v41
	v_mov_b32_e32 v37, v45
	v_mov_b32_e32 v41, v56
	v_mov_b32_e32 v45, v57
	v_mov_b32_e32 v56, v67
	v_mov_b32_e32 v57, v68
	v_mov_b32_e32 v67, v69
	v_pk_add_f32 v[10:11], v[74:75], v[10:11]
	v_pk_add_f32 v[12:13], v[12:13], v[14:15]
	v_pk_add_f32 v[14:15], v[20:21], v[22:23]
	v_pk_add_f32 v[22:23], v[28:29], v[34:35]
	v_pk_add_f32 v[34:35], v[56:57], v[66:67]
	v_pk_add_f32 v[10:11], v[10:11], v[10:11] op_sel:[0,1] op_sel_hi:[1,0]
	v_add_f32_e32 v16, v34, v35
	v_mov_b32_e32 v17, v18
	v_mov_b32_e32 v11, v19
	v_add_f32_e32 v16, 0, v16
	v_pk_add_f32 v[10:11], v[16:17], v[10:11]
	v_pk_add_f32 v[14:15], v[14:15], v[14:15] op_sel:[0,1] op_sel_hi:[1,0]
	v_pk_add_f32 v[10:11], v[10:11], v[12:13]
	v_mov_b32_e32 v25, v32
	v_pk_add_f32 v[10:11], v[10:11], v[10:11] op_sel:[0,1] op_sel_hi:[1,0]
	v_mov_b32_e32 v27, v33
	v_mov_b32_e32 v15, v31
	v_mov_b32_e32 v11, v30
	v_pk_add_f32 v[20:21], v[24:25], v[26:27]
	v_pk_add_f32 v[10:11], v[10:11], v[14:15]
	v_pk_add_f32 v[22:23], v[22:23], v[22:23] op_sel:[0,1] op_sel_hi:[1,0]
	v_pk_add_f32 v[10:11], v[10:11], v[20:21]
	v_add_f32_e32 v32, v38, v39
	v_pk_add_f32 v[10:11], v[10:11], v[10:11] op_sel:[0,1] op_sel_hi:[1,0]
	v_mov_b32_e32 v33, v44
	v_mov_b32_e32 v23, v43
	v_mov_b32_e32 v11, v42
	v_mov_b32_e32 v38, v47
	v_mov_b32_e32 v39, v48
	v_mov_b32_e32 v47, v49
	v_pk_add_f32 v[24:25], v[32:33], v[36:37]
	v_pk_add_f32 v[10:11], v[10:11], v[22:23]
	v_pk_add_f32 v[26:27], v[38:39], v[46:47]
	v_pk_add_f32 v[10:11], v[10:11], v[24:25]
	v_pk_add_f32 v[26:27], v[26:27], v[26:27] op_sel:[0,1] op_sel_hi:[1,0]
	v_pk_add_f32 v[10:11], v[10:11], v[10:11] op_sel:[0,1] op_sel_hi:[1,0]
	v_add_f32_e32 v40, v50, v51
	v_add_f32_e32 v44, v52, v53
	v_mov_b32_e32 v27, v55
	v_mov_b32_e32 v11, v54
	v_mov_b32_e32 v48, v63
	v_mov_b32_e32 v49, v64
	v_mov_b32_e32 v63, v65
	v_pk_add_f32 v[28:29], v[40:41], v[44:45]
	v_pk_add_f32 v[10:11], v[10:11], v[26:27]
	v_pk_add_f32 v[32:33], v[48:49], v[62:63]
	v_pk_add_f32 v[10:11], v[10:11], v[28:29]
	v_pk_add_f32 v[32:33], v[32:33], v[32:33] op_sel:[0,1] op_sel_hi:[1,0]
	v_pk_add_f32 v[10:11], v[10:11], v[10:11] op_sel:[0,1] op_sel_hi:[1,0]
	v_add_f32_e32 v50, v58, v59
	v_add_f32_e32 v52, v60, v61
	v_mov_b32_e32 v51, v72
	v_mov_b32_e32 v53, v73
	v_mov_b32_e32 v33, v71
	v_mov_b32_e32 v11, v70
	v_pk_add_f32 v[10:11], v[10:11], v[32:33]
	v_pk_add_f32 v[12:13], v[50:51], v[52:53]
	s_nop 0
	v_pk_add_f32 v[10:11], v[10:11], v[12:13]
	s_nop 0
	v_add_f32_e32 v10, v10, v11
	v_fmamk_f32 v10, v10, 0x39800000, v232
	v_rsq_f32_e32 v10, v10
	ds_write_b32 v76, v10
.Lst_p2end:
	s_ashr_i32 s4, s2, 8
	s_cmp_eq_u32 s4, 1
	s_cselect_b64 s[88:89], -1, 0
	s_cmp_lg_u32 s4, 1
	s_mov_b32 s43, s87
	s_cbranch_scc1 .LBB0_133
	s_barrier
